# v71 with the final f32 output stores of the last FFN-down epilogue as default-policy stores instead of non-temporal
# speedup vs baseline: 1.0284x; 1.0284x over previous
;     __device__ __forceinline__ void row_out(const f32x4 v0, const f32x4 v1, int row, int col, float& ss) const {
;         if (C) { float* rowp = C + (size_t)row * ldc + col; __builtin_nontemporal_store(v0, (f32x4*)rowp); __builtin_nontemporal_store(v1, (f32x4*)(rowp + 4)); }
;     __device__ __forceinline__ void operator()(const f32x4 (&acc)[2][2][4][2], const Unit& u, int wr, int wc, int fr, int fq) const {
;     ...
;                 for (int mm = 0; mm < 2; ++mm) { const int row = row0 + ai * HALF + (mh + mm) * 16;
; #pragma unroll
;                     for (int bj = 0; bj < 2; ++bj) if (bj == 0 || !u.q) rw[mm][bj] = *(const u32x4*)(XB0 + (size_t)row * ldc + col0 + bj * HALF); }
; #pragma unroll
;                 for (int mm = 0; mm < 2; ++mm) { const int m = mh + mm, row = row0 + ai * HALF + m * 16; float ss = 0.f;
; #pragma unroll
;                     for (int bj = 0; bj < 2; ++bj) if (bj == 0 || !u.q) { const u32x4 w = rw[mm][bj];
;                         const f32x4 v0 = acc[ai][bj][m][0] + (f32x4){bf_lo(w.x), bf_hi(w.x), bf_lo(w.y), bf_hi(w.y)}, v1 = acc[ai][bj][m][1] + (f32x4){bf_lo(w.z), bf_hi(w.z), bf_lo(w.w), bf_hi(w.w)};
;                         row_out(v0, v1, row, col0 + bj * HALF, ss); }
.LBB0_3232:
	v_mov_b32_e32 v144, v151
	v_mov_b32_e32 v146, v150
	s_andn2_b64 vcc, exec, s[12:13]
	s_cbranch_vccnz .LBB0_3234
	s_add_i32 s16, s40, s30
	v_add_u32_e32 v144, s16, v144
	s_add_i32 s16, s41, s31
	v_lshl_add_u32 v148, v146, 3, s16
	v_ashrrev_i32_e32 v145, 31, v144
	v_ashrrev_i32_e32 v149, 31, v148
	v_lshl_add_u64 v[146:147], v[148:149], 1, s[96:97]
	v_lshlrev_b64 v[156:157], 11, v[144:145]
	v_lshl_add_u64 v[160:161], v[146:147], 0, v[156:157]
	v_add_u32_e32 v172, 16, v144
	global_load_dwordx4 v[156:159], v[160:161], off
	s_nop 0
	global_load_dwordx4 v[160:163], v[160:161], off offset:256
	v_ashrrev_i32_e32 v173, 31, v172
	v_lshlrev_b64 v[164:165], 11, v[172:173]
	v_lshl_add_u64 v[168:169], v[146:147], 0, v[164:165]
	global_load_dwordx4 v[164:167], v[168:169], off
	s_nop 0
	global_load_dwordx4 v[168:171], v[168:169], off offset:256
	v_lshlrev_b64 v[176:177], 12, v[144:145]
	v_lshlrev_b64 v[148:149], 2, v[148:149]
	v_lshl_add_u64 v[176:177], s[92:93], 0, v[176:177]
	v_lshlrev_b64 v[172:173], 12, v[172:173]
	v_lshl_add_u64 v[176:177], v[176:177], 0, v[148:149]
	v_add_u32_e32 v174, 32, v144
	v_lshl_add_u64 v[172:173], s[92:93], 0, v[172:173]
	v_ashrrev_i32_e32 v175, 31, v174
	v_lshl_add_u64 v[172:173], v[172:173], 0, v[148:149]
	v_lshlrev_b64 v[178:179], 11, v[174:175]
	v_lshl_add_u64 v[178:179], v[146:147], 0, v[178:179]
	s_waitcnt vmcnt(0)
	v_lshlrev_b32_e32 v182, 16, v156
	v_and_b32_e32 v183, 0xffff0000, v156
	v_lshlrev_b32_e32 v156, 16, v157
	v_and_b32_e32 v157, 0xffff0000, v157
	v_lshlrev_b32_e32 v186, 16, v160
	v_and_b32_e32 v187, 0xffff0000, v160
	v_lshlrev_b32_e32 v180, 16, v158
	v_and_b32_e32 v181, 0xffff0000, v158
	v_lshlrev_b32_e32 v158, 16, v159
	v_and_b32_e32 v159, 0xffff0000, v159
	v_lshlrev_b32_e32 v184, 16, v162
	v_and_b32_e32 v185, 0xffff0000, v162
	v_lshlrev_b32_e32 v162, 16, v163
	v_and_b32_e32 v163, 0xffff0000, v163
	v_lshlrev_b32_e32 v160, 16, v161
	v_and_b32_e32 v161, 0xffff0000, v161
	v_pk_add_f32 v[126:127], v[126:127], v[156:157]
	v_pk_add_f32 v[124:125], v[124:125], v[182:183]
	v_pk_add_f32 v[112:113], v[112:113], v[186:187]
	v_pk_add_f32 v[122:123], v[122:123], v[158:159]
	v_pk_add_f32 v[120:121], v[120:121], v[180:181]
	v_pk_add_f32 v[106:107], v[106:107], v[162:163]
	v_pk_add_f32 v[104:105], v[104:105], v[184:185]
	v_pk_add_f32 v[114:115], v[114:115], v[160:161]
	v_lshlrev_b32_e32 v156, 16, v166
	v_and_b32_e32 v157, 0xffff0000, v166
	v_lshlrev_b32_e32 v158, 16, v167
	v_and_b32_e32 v159, 0xffff0000, v167
	v_lshlrev_b32_e32 v160, 16, v164
	v_and_b32_e32 v161, 0xffff0000, v164
	v_lshlrev_b32_e32 v162, 16, v165
	v_and_b32_e32 v163, 0xffff0000, v165
	global_store_dwordx4 v[176:177], v[124:127], off
	global_store_dwordx4 v[176:177], v[120:123], off offset:16
	global_store_dwordx4 v[176:177], v[112:115], off offset:512
	global_store_dwordx4 v[176:177], v[104:107], off offset:528
	v_lshlrev_b32_e32 v164, 16, v170
	v_add_u32_e32 v112, 48, v144
	v_and_b32_e32 v165, 0xffff0000, v170
	v_lshlrev_b32_e32 v166, 16, v171
	v_and_b32_e32 v167, 0xffff0000, v171
	v_lshlrev_b32_e32 v170, 16, v168
	v_and_b32_e32 v171, 0xffff0000, v168
	v_lshlrev_b32_e32 v168, 16, v169
	v_and_b32_e32 v169, 0xffff0000, v169
	v_pk_add_f32 v[106:107], v[110:111], v[158:159]
	v_pk_add_f32 v[104:105], v[108:109], v[156:157]
	v_pk_add_f32 v[110:111], v[118:119], v[162:163]
	v_pk_add_f32 v[108:109], v[116:117], v[160:161]
	v_ashrrev_i32_e32 v113, 31, v112
	v_pk_add_f32 v[98:99], v[98:99], v[166:167]
	v_pk_add_f32 v[96:97], v[96:97], v[164:165]
	v_pk_add_f32 v[102:103], v[102:103], v[168:169]
	v_pk_add_f32 v[100:101], v[100:101], v[170:171]
	global_store_dwordx4 v[172:173], v[108:111], off
	global_store_dwordx4 v[172:173], v[104:107], off offset:16
	global_store_dwordx4 v[172:173], v[100:103], off offset:512
	global_store_dwordx4 v[172:173], v[96:99], off offset:528
	v_lshlrev_b64 v[104:105], 11, v[112:113]
	v_lshl_add_u64 v[108:109], v[146:147], 0, v[104:105]
	global_load_dwordx4 v[96:99], v[178:179], off
	global_load_dwordx4 v[100:103], v[178:179], off offset:256
	global_load_dwordx4 v[104:107], v[108:109], off
	s_nop 0
	global_load_dwordx4 v[108:111], v[108:109], off offset:256
	v_lshlrev_b64 v[116:117], 12, v[174:175]
	v_lshlrev_b64 v[112:113], 12, v[112:113]
	v_lshl_add_u64 v[116:117], s[92:93], 0, v[116:117]
	v_lshl_add_u64 v[112:113], s[92:93], 0, v[112:113]
	v_lshl_add_u64 v[116:117], v[116:117], 0, v[148:149]
	v_add_u32_e32 v114, 0x80, v144
	v_lshl_add_u64 v[112:113], v[112:113], 0, v[148:149]
	v_ashrrev_i32_e32 v115, 31, v114
	v_lshlrev_b64 v[118:119], 11, v[114:115]
	v_lshl_add_u64 v[118:119], v[146:147], 0, v[118:119]
	s_waitcnt vmcnt(3)
	v_lshlrev_b32_e32 v122, 16, v96
	v_and_b32_e32 v123, 0xffff0000, v96
	v_lshlrev_b32_e32 v96, 16, v97
	v_and_b32_e32 v97, 0xffff0000, v97
	s_waitcnt vmcnt(1)
	v_lshlrev_b32_e32 v156, 16, v106
	v_and_b32_e32 v157, 0xffff0000, v106
	v_lshlrev_b32_e32 v120, 16, v98
	v_and_b32_e32 v121, 0xffff0000, v98
	v_lshlrev_b32_e32 v98, 16, v99
	v_and_b32_e32 v99, 0xffff0000, v99
	v_lshlrev_b32_e32 v124, 16, v102
	v_and_b32_e32 v125, 0xffff0000, v102
	v_lshlrev_b32_e32 v102, 16, v103
	v_and_b32_e32 v103, 0xffff0000, v103
	v_lshlrev_b32_e32 v126, 16, v100
	v_and_b32_e32 v127, 0xffff0000, v100
	v_lshlrev_b32_e32 v100, 16, v101
	v_and_b32_e32 v101, 0xffff0000, v101
	v_lshlrev_b32_e32 v106, 16, v107
	v_and_b32_e32 v107, 0xffff0000, v107
	v_lshlrev_b32_e32 v158, 16, v104
	v_and_b32_e32 v159, 0xffff0000, v104
	v_lshlrev_b32_e32 v104, 16, v105
	v_and_b32_e32 v105, 0xffff0000, v105
	s_waitcnt vmcnt(0)
;     __device__ __forceinline__ void row_out(const f32x4 v0, const f32x4 v1, int row, int col, float& ss) const {
;         if (C) { float* rowp = C + (size_t)row * ldc + col; __builtin_nontemporal_store(v0, (f32x4*)rowp); __builtin_nontemporal_store(v1, (f32x4*)(rowp + 4)); }
;     __device__ __forceinline__ void operator()(const f32x4 (&acc)[2][2][4][2], const Unit& u, int wr, int wc, int fr, int fq) const {
;     ...
;                 for (int mm = 0; mm < 2; ++mm) { const int row = row0 + ai * HALF + (mh + mm) * 16;
; #pragma unroll
;                     for (int bj = 0; bj < 2; ++bj) if (bj == 0 || !u.q) rw[mm][bj] = *(const u32x4*)(XB0 + (size_t)row * ldc + col0 + bj * HALF); }
; #pragma unroll
;                 for (int mm = 0; mm < 2; ++mm) { const int m = mh + mm, row = row0 + ai * HALF + m * 16; float ss = 0.f;
; #pragma unroll
;                     for (int bj = 0; bj < 2; ++bj) if (bj == 0 || !u.q) { const u32x4 w = rw[mm][bj];
;                         const f32x4 v0 = acc[ai][bj][m][0] + (f32x4){bf_lo(w.x), bf_hi(w.x), bf_lo(w.y), bf_hi(w.y)}, v1 = acc[ai][bj][m][1] + (f32x4){bf_lo(w.z), bf_hi(w.z), bf_lo(w.w), bf_hi(w.w)};
;                         row_out(v0, v1, row, col0 + bj * HALF, ss); }
	v_lshlrev_b32_e32 v160, 16, v110
	v_and_b32_e32 v161, 0xffff0000, v110
	v_lshlrev_b32_e32 v110, 16, v111
	v_and_b32_e32 v111, 0xffff0000, v111
	v_lshlrev_b32_e32 v162, 16, v108
	v_and_b32_e32 v163, 0xffff0000, v108
	v_lshlrev_b32_e32 v108, 16, v109
	v_and_b32_e32 v109, 0xffff0000, v109
	v_pk_add_f32 v[94:95], v[94:95], v[96:97]
	v_pk_add_f32 v[92:93], v[92:93], v[122:123]
	v_pk_add_f32 v[80:81], v[80:81], v[156:157]
	v_pk_add_f32 v[90:91], v[90:91], v[98:99]
	v_pk_add_f32 v[88:89], v[88:89], v[120:121]
	v_pk_add_f32 v[74:75], v[74:75], v[102:103]
	v_pk_add_f32 v[72:73], v[72:73], v[124:125]
	v_pk_add_f32 v[78:79], v[78:79], v[100:101]
	v_pk_add_f32 v[76:77], v[76:77], v[126:127]
	v_pk_add_f32 v[82:83], v[82:83], v[106:107]
	v_pk_add_f32 v[86:87], v[86:87], v[104:105]
	v_pk_add_f32 v[84:85], v[84:85], v[158:159]
	v_pk_add_f32 v[66:67], v[66:67], v[110:111]
	v_pk_add_f32 v[64:65], v[64:65], v[160:161]
	v_pk_add_f32 v[70:71], v[70:71], v[108:109]
	v_pk_add_f32 v[68:69], v[68:69], v[162:163]
	global_store_dwordx4 v[116:117], v[92:95], off
	global_store_dwordx4 v[116:117], v[88:91], off offset:16
	global_store_dwordx4 v[116:117], v[76:79], off offset:512
	global_store_dwordx4 v[116:117], v[72:75], off offset:528
	global_store_dwordx4 v[112:113], v[84:87], off
	global_store_dwordx4 v[112:113], v[80:83], off offset:16
	global_store_dwordx4 v[112:113], v[68:71], off offset:512
	global_store_dwordx4 v[112:113], v[64:67], off offset:528
	v_add_u32_e32 v80, 0x90, v144
	v_ashrrev_i32_e32 v81, 31, v80
	v_lshlrev_b64 v[72:73], 11, v[80:81]
	v_lshl_add_u64 v[76:77], v[146:147], 0, v[72:73]
	global_load_dwordx4 v[64:67], v[118:119], off
	global_load_dwordx4 v[68:71], v[118:119], off offset:256
	global_load_dwordx4 v[72:75], v[76:77], off
	s_nop 0
	global_load_dwordx4 v[76:79], v[76:77], off offset:256
	v_lshlrev_b64 v[84:85], 12, v[114:115]
	v_lshlrev_b64 v[80:81], 12, v[80:81]
	v_lshl_add_u64 v[84:85], s[92:93], 0, v[84:85]
	v_lshl_add_u64 v[80:81], s[92:93], 0, v[80:81]
	v_lshl_add_u64 v[84:85], v[84:85], 0, v[148:149]
	v_add_u32_e32 v82, 0xa0, v144
	v_lshl_add_u64 v[80:81], v[80:81], 0, v[148:149]
	v_ashrrev_i32_e32 v83, 31, v82
	v_lshlrev_b64 v[86:87], 11, v[82:83]
	v_lshl_add_u64 v[86:87], v[146:147], 0, v[86:87]
	s_waitcnt vmcnt(3)
	v_lshlrev_b32_e32 v90, 16, v64
	v_and_b32_e32 v91, 0xffff0000, v64
	v_lshlrev_b32_e32 v64, 16, v65
	v_and_b32_e32 v65, 0xffff0000, v65
	s_waitcnt vmcnt(1)
	v_lshlrev_b32_e32 v96, 16, v74
	v_and_b32_e32 v97, 0xffff0000, v74
	v_lshlrev_b32_e32 v88, 16, v66
	v_and_b32_e32 v89, 0xffff0000, v66
	v_lshlrev_b32_e32 v66, 16, v67
	v_and_b32_e32 v67, 0xffff0000, v67
	v_lshlrev_b32_e32 v92, 16, v70
	v_and_b32_e32 v93, 0xffff0000, v70
	v_lshlrev_b32_e32 v70, 16, v71
	v_and_b32_e32 v71, 0xffff0000, v71
	v_lshlrev_b32_e32 v94, 16, v68
	v_and_b32_e32 v95, 0xffff0000, v68
	v_lshlrev_b32_e32 v68, 16, v69
	v_and_b32_e32 v69, 0xffff0000, v69
	v_lshlrev_b32_e32 v74, 16, v75
	v_and_b32_e32 v75, 0xffff0000, v75
	v_lshlrev_b32_e32 v98, 16, v72
	v_and_b32_e32 v99, 0xffff0000, v72
	v_lshlrev_b32_e32 v72, 16, v73
	v_and_b32_e32 v73, 0xffff0000, v73
	s_waitcnt vmcnt(0)
;     __device__ __forceinline__ void row_out(const f32x4 v0, const f32x4 v1, int row, int col, float& ss) const {
;         if (C) { float* rowp = C + (size_t)row * ldc + col; __builtin_nontemporal_store(v0, (f32x4*)rowp); __builtin_nontemporal_store(v1, (f32x4*)(rowp + 4)); }
;     __device__ __forceinline__ void operator()(const f32x4 (&acc)[2][2][4][2], const Unit& u, int wr, int wc, int fr, int fq) const {
;     ...
;                 for (int mm = 0; mm < 2; ++mm) { const int row = row0 + ai * HALF + (mh + mm) * 16;
; #pragma unroll
;                     for (int bj = 0; bj < 2; ++bj) if (bj == 0 || !u.q) rw[mm][bj] = *(const u32x4*)(XB0 + (size_t)row * ldc + col0 + bj * HALF); }
; #pragma unroll
;                 for (int mm = 0; mm < 2; ++mm) { const int m = mh + mm, row = row0 + ai * HALF + m * 16; float ss = 0.f;
; #pragma unroll
;                     for (int bj = 0; bj < 2; ++bj) if (bj == 0 || !u.q) { const u32x4 w = rw[mm][bj];
;                         const f32x4 v0 = acc[ai][bj][m][0] + (f32x4){bf_lo(w.x), bf_hi(w.x), bf_lo(w.y), bf_hi(w.y)}, v1 = acc[ai][bj][m][1] + (f32x4){bf_lo(w.z), bf_hi(w.z), bf_lo(w.w), bf_hi(w.w)};
;                         row_out(v0, v1, row, col0 + bj * HALF, ss); }
	v_lshlrev_b32_e32 v100, 16, v78
	v_and_b32_e32 v101, 0xffff0000, v78
	v_lshlrev_b32_e32 v78, 16, v79
	v_and_b32_e32 v79, 0xffff0000, v79
	v_lshlrev_b32_e32 v102, 16, v76
	v_and_b32_e32 v103, 0xffff0000, v76
	v_lshlrev_b32_e32 v76, 16, v77
	v_and_b32_e32 v77, 0xffff0000, v77
	v_pk_add_f32 v[62:63], v[62:63], v[64:65]
	v_pk_add_f32 v[60:61], v[60:61], v[90:91]
	v_pk_add_f32 v[48:49], v[48:49], v[96:97]
	v_pk_add_f32 v[58:59], v[58:59], v[66:67]
	v_pk_add_f32 v[56:57], v[56:57], v[88:89]
	v_pk_add_f32 v[42:43], v[42:43], v[70:71]
	v_pk_add_f32 v[40:41], v[40:41], v[92:93]
	v_pk_add_f32 v[46:47], v[46:47], v[68:69]
	v_pk_add_f32 v[44:45], v[44:45], v[94:95]
	v_pk_add_f32 v[50:51], v[50:51], v[74:75]
	v_pk_add_f32 v[54:55], v[54:55], v[72:73]
	v_pk_add_f32 v[52:53], v[52:53], v[98:99]
	v_pk_add_f32 v[34:35], v[34:35], v[78:79]
	v_pk_add_f32 v[32:33], v[32:33], v[100:101]
	v_pk_add_f32 v[38:39], v[38:39], v[76:77]
	v_pk_add_f32 v[36:37], v[36:37], v[102:103]
	global_store_dwordx4 v[84:85], v[60:63], off
	global_store_dwordx4 v[84:85], v[56:59], off offset:16
	global_store_dwordx4 v[84:85], v[44:47], off offset:512
	global_store_dwordx4 v[84:85], v[40:43], off offset:528
	global_store_dwordx4 v[80:81], v[52:55], off
	global_store_dwordx4 v[80:81], v[48:51], off offset:16
	global_store_dwordx4 v[80:81], v[36:39], off offset:512
	global_store_dwordx4 v[80:81], v[32:35], off offset:528
	v_add_u32_e32 v48, 0xb0, v144
	v_ashrrev_i32_e32 v49, 31, v48
	v_lshlrev_b64 v[40:41], 11, v[48:49]
	v_lshl_add_u64 v[44:45], v[146:147], 0, v[40:41]
	global_load_dwordx4 v[32:35], v[86:87], off
	global_load_dwordx4 v[36:39], v[86:87], off offset:256
	global_load_dwordx4 v[40:43], v[44:45], off
	s_nop 0
	global_load_dwordx4 v[44:47], v[44:45], off offset:256
	v_lshlrev_b64 v[50:51], 12, v[82:83]
	v_lshlrev_b64 v[48:49], 12, v[48:49]
	v_lshl_add_u64 v[50:51], s[92:93], 0, v[50:51]
	v_lshl_add_u64 v[48:49], s[92:93], 0, v[48:49]
	v_lshl_add_u64 v[50:51], v[50:51], 0, v[148:149]
	v_lshl_add_u64 v[48:49], v[48:49], 0, v[148:149]
	s_waitcnt vmcnt(3)
	v_lshlrev_b32_e32 v54, 16, v32
	v_and_b32_e32 v55, 0xffff0000, v32
	v_lshlrev_b32_e32 v32, 16, v33
	v_and_b32_e32 v33, 0xffff0000, v33
	v_lshlrev_b32_e32 v52, 16, v34
	v_and_b32_e32 v53, 0xffff0000, v34
	v_lshlrev_b32_e32 v34, 16, v35
	v_and_b32_e32 v35, 0xffff0000, v35
	s_waitcnt vmcnt(2)
	v_lshlrev_b32_e32 v56, 16, v38
	v_and_b32_e32 v57, 0xffff0000, v38
	v_lshlrev_b32_e32 v38, 16, v39
	v_and_b32_e32 v39, 0xffff0000, v39
	v_lshlrev_b32_e32 v58, 16, v36
	v_and_b32_e32 v59, 0xffff0000, v36
	v_lshlrev_b32_e32 v36, 16, v37
	v_and_b32_e32 v37, 0xffff0000, v37
	s_waitcnt vmcnt(1)
	v_lshlrev_b32_e32 v60, 16, v42
	v_and_b32_e32 v61, 0xffff0000, v42
	v_lshlrev_b32_e32 v42, 16, v43
	v_and_b32_e32 v43, 0xffff0000, v43
	v_lshlrev_b32_e32 v62, 16, v40
	v_and_b32_e32 v63, 0xffff0000, v40
	v_lshlrev_b32_e32 v40, 16, v41
	v_and_b32_e32 v41, 0xffff0000, v41
	s_waitcnt vmcnt(0)
	v_lshlrev_b32_e32 v64, 16, v46
	v_and_b32_e32 v65, 0xffff0000, v46
	v_lshlrev_b32_e32 v46, 16, v47
	v_and_b32_e32 v47, 0xffff0000, v47
	v_lshlrev_b32_e32 v66, 16, v44
	v_and_b32_e32 v67, 0xffff0000, v44
	v_lshlrev_b32_e32 v44, 16, v45
	v_and_b32_e32 v45, 0xffff0000, v45
	v_pk_add_f32 v[30:31], v[30:31], v[32:33]
	v_pk_add_f32 v[28:29], v[28:29], v[54:55]
	v_pk_add_f32 v[26:27], v[26:27], v[34:35]
	v_pk_add_f32 v[24:25], v[24:25], v[52:53]
	v_pk_add_f32 v[10:11], v[10:11], v[38:39]
	v_pk_add_f32 v[8:9], v[8:9], v[56:57]
	v_pk_add_f32 v[14:15], v[14:15], v[36:37]
	v_pk_add_f32 v[12:13], v[12:13], v[58:59]
	v_pk_add_f32 v[18:19], v[18:19], v[42:43]
	v_pk_add_f32 v[16:17], v[16:17], v[60:61]
	v_pk_add_f32 v[22:23], v[22:23], v[40:41]
	v_pk_add_f32 v[20:21], v[20:21], v[62:63]
	v_pk_add_f32 v[2:3], v[2:3], v[46:47]
	v_pk_add_f32 v[0:1], v[0:1], v[64:65]
	v_pk_add_f32 v[6:7], v[6:7], v[44:45]
	v_pk_add_f32 v[4:5], v[4:5], v[66:67]
	global_store_dwordx4 v[50:51], v[28:31], off
	global_store_dwordx4 v[50:51], v[24:27], off offset:16
	global_store_dwordx4 v[50:51], v[12:15], off offset:512
	global_store_dwordx4 v[50:51], v[8:11], off offset:528
	global_store_dwordx4 v[48:49], v[20:23], off
	global_store_dwordx4 v[48:49], v[16:19], off offset:16
	global_store_dwordx4 v[48:49], v[4:7], off offset:512
	global_store_dwordx4 v[48:49], v[0:3], off offset:528

;     __device__ __forceinline__ void row_out(const f32x4 v0, const f32x4 v1, int row, int col, float& ss) const {
;         if (C) { float* rowp = C + (size_t)row * ldc + col; __builtin_nontemporal_store(v0, (f32x4*)rowp); __builtin_nontemporal_store(v1, (f32x4*)(rowp + 4)); }
;     __device__ __forceinline__ void operator()(const f32x4 (&acc)[2][2][4][2], const Unit& u, int wr, int wc, int fr, int fq) const {
;     ...
;                 for (int mm = 0; mm < 2; ++mm) { const int row = row0 + ai * HALF + (mh + mm) * 16;
; #pragma unroll
;                     for (int bj = 0; bj < 2; ++bj) if (bj == 0 || !u.q) rw[mm][bj] = *(const u32x4*)(XB0 + (size_t)row * ldc + col0 + bj * HALF); }
; #pragma unroll
;                 for (int mm = 0; mm < 2; ++mm) { const int m = mh + mm, row = row0 + ai * HALF + m * 16; float ss = 0.f;
; #pragma unroll
;                     for (int bj = 0; bj < 2; ++bj) if (bj == 0 || !u.q) { const u32x4 w = rw[mm][bj];
;                         const f32x4 v0 = acc[ai][bj][m][0] + (f32x4){bf_lo(w.x), bf_hi(w.x), bf_lo(w.y), bf_hi(w.y)}, v1 = acc[ai][bj][m][1] + (f32x4){bf_lo(w.z), bf_hi(w.z), bf_lo(w.w), bf_hi(w.w)};
;                         row_out(v0, v1, row, col0 + bj * HALF, ss); }
.LBB0_3251:
	s_and_b64 vcc, exec, s[4:5]
	s_cbranch_vccz .LBB0_3240
	v_mov_b32_e32 v1, v86
	v_mov_b32_e32 v2, v87
	s_and_b64 vcc, exec, s[2:3]
	s_cbranch_vccz .LBB0_3240
	s_lshl_b32 s0, s12, 6
	s_or_b32 s0, s0, s18
	v_lshl_add_u32 v2, v2, 3, s0
	s_waitcnt vmcnt(2)
	v_add_u32_e32 v38, s20, v1
	v_ashrrev_i32_e32 v3, 31, v2
	v_ashrrev_i32_e32 v39, 31, v38
	s_waitcnt vmcnt(0)
	v_add_u32_e32 v44, 16, v38
	v_lshl_add_u64 v[36:37], v[2:3], 1, s[96:97]
	v_lshlrev_b64 v[28:29], 11, v[38:39]
	v_ashrrev_i32_e32 v45, 31, v44
	v_lshl_add_u64 v[28:29], v[36:37], 0, v[28:29]
	v_lshlrev_b64 v[32:33], 11, v[44:45]
	global_load_dwordx4 v[28:31], v[28:29], off
	v_lshl_add_u64 v[32:33], v[36:37], 0, v[32:33]
	global_load_dwordx4 v[32:35], v[32:33], off
	v_lshlrev_b64 v[52:53], 12, v[38:39]
	v_lshl_add_u64 v[52:53], s[92:93], 0, v[52:53]
	v_lshlrev_b64 v[44:45], 12, v[44:45]
	v_lshlrev_b64 v[2:3], 2, v[2:3]
	v_add_u32_e32 v46, 32, v38
	v_lshl_add_u64 v[44:45], s[92:93], 0, v[44:45]
	v_lshl_add_u64 v[52:53], v[52:53], 0, v[2:3]
	v_ashrrev_i32_e32 v47, 31, v46
	v_lshl_add_u64 v[44:45], v[44:45], 0, v[2:3]
	v_lshlrev_b64 v[54:55], 11, v[46:47]
	v_lshl_add_u64 v[54:55], v[36:37], 0, v[54:55]
	s_waitcnt vmcnt(1)
	v_lshlrev_b32_e32 v56, 16, v30
	v_and_b32_e32 v57, 0xffff0000, v30
	v_lshlrev_b32_e32 v58, 16, v28
	v_and_b32_e32 v59, 0xffff0000, v28
	v_lshlrev_b32_e32 v60, 16, v29
	v_and_b32_e32 v61, 0xffff0000, v29
	v_lshlrev_b32_e32 v30, 16, v31
	v_and_b32_e32 v31, 0xffff0000, v31
	s_waitcnt vmcnt(0)
	v_lshlrev_b32_e32 v62, 16, v34
	v_and_b32_e32 v63, 0xffff0000, v34
	v_lshlrev_b32_e32 v64, 16, v35
	v_and_b32_e32 v65, 0xffff0000, v35
	v_lshlrev_b32_e32 v66, 16, v32
	v_and_b32_e32 v67, 0xffff0000, v32
	v_lshlrev_b32_e32 v80, 16, v33
	v_and_b32_e32 v81, 0xffff0000, v33
	v_pk_add_f32 v[28:29], v[40:41], v[56:57]
	v_pk_add_f32 v[34:35], v[50:51], v[60:61]
	v_pk_add_f32 v[32:33], v[48:49], v[58:59]
	v_pk_add_f32 v[30:31], v[42:43], v[30:31]
	v_pk_add_f32 v[26:27], v[26:27], v[64:65]
	v_pk_add_f32 v[24:25], v[24:25], v[62:63]
	v_pk_add_f32 v[22:23], v[22:23], v[80:81]
	v_pk_add_f32 v[20:21], v[20:21], v[66:67]
	global_store_dwordx4 v[52:53], v[32:35], off
	global_store_dwordx4 v[52:53], v[28:31], off offset:16
	global_store_dwordx4 v[44:45], v[20:23], off
	global_store_dwordx4 v[44:45], v[24:27], off offset:16
	v_add_u32_e32 v28, 48, v38
	v_ashrrev_i32_e32 v29, 31, v28
	v_lshlrev_b64 v[24:25], 11, v[28:29]
	global_load_dwordx4 v[20:23], v[54:55], off
	v_lshl_add_u64 v[24:25], v[36:37], 0, v[24:25]
	global_load_dwordx4 v[24:27], v[24:25], off
	v_lshlrev_b64 v[30:31], 12, v[46:47]
	v_lshlrev_b64 v[28:29], 12, v[28:29]
	v_lshl_add_u64 v[30:31], s[92:93], 0, v[30:31]
	v_lshl_add_u64 v[28:29], s[92:93], 0, v[28:29]
	v_lshl_add_u64 v[30:31], v[30:31], 0, v[2:3]
	v_lshl_add_u64 v[2:3], v[28:29], 0, v[2:3]
	s_waitcnt vmcnt(1)
	v_lshlrev_b32_e32 v32, 16, v20
	v_and_b32_e32 v33, 0xffff0000, v20
	v_lshlrev_b32_e32 v20, 16, v21
	v_and_b32_e32 v21, 0xffff0000, v21
	v_lshlrev_b32_e32 v28, 16, v22
	v_and_b32_e32 v29, 0xffff0000, v22
	v_lshlrev_b32_e32 v22, 16, v23
	v_and_b32_e32 v23, 0xffff0000, v23
	s_waitcnt vmcnt(0)
	v_lshlrev_b32_e32 v34, 16, v26
	v_and_b32_e32 v35, 0xffff0000, v26
	v_lshlrev_b32_e32 v26, 16, v27
	v_and_b32_e32 v27, 0xffff0000, v27
	v_lshlrev_b32_e32 v36, 16, v24
	v_and_b32_e32 v37, 0xffff0000, v24
	v_lshlrev_b32_e32 v24, 16, v25
	v_and_b32_e32 v25, 0xffff0000, v25
	v_pk_add_f32 v[14:15], v[14:15], v[20:21]
	v_pk_add_f32 v[12:13], v[12:13], v[32:33]
	v_pk_add_f32 v[18:19], v[18:19], v[22:23]
	v_pk_add_f32 v[16:17], v[16:17], v[28:29]
	v_pk_add_f32 v[10:11], v[10:11], v[26:27]
	v_pk_add_f32 v[8:9], v[8:9], v[34:35]
	v_pk_add_f32 v[6:7], v[6:7], v[24:25]
	v_pk_add_f32 v[4:5], v[4:5], v[36:37]
	global_store_dwordx4 v[30:31], v[12:15], off
	global_store_dwordx4 v[30:31], v[16:19], off offset:16
	global_store_dwordx4 v[2:3], v[4:7], off
	global_store_dwordx4 v[2:3], v[8:11], off offset:16
	s_branch .LBB0_3240
